# attention: bias table padded with -1e30 on both sides; interior query blocks (full +-64 band) take a fast path with one fma per score instead of add/compare/fma/select (results identical)
# speedup vs baseline: 1.0022x; 1.0022x over previous
; #define TIDX tid_opaque()
; __device__ void attn_phase(unsigned char* smem, const Params& p, int chunk) {
;     ...
;     const int tid = TIDX, lane = tid & 63, w = tid >> 6, half = w >> 2, qs = w & 3, r16 = lane & 15, g4 = lane >> 4;
;     bf16_t* Ks = (bf16_t*)smem; bf16_t* Vs = (bf16_t*)(smem + AKR * KST * 2); float* bs = (float*)(smem + AKR * KST * 2 + AKR * VSR * 2);
;     const int npair = NB * 24 * 32 / 2;
;     u32x4 kreg[5], vreg[5]; bf16x8 qn[2]; float bn = 0.f;
;     ...
;     const int nrep = ((REP >> 5) & 1) + 1;
;     int pair_ = blockIdx.x;
;     if (pair_ < npair * nrep) ATT_PREFETCH(pair_ % npair);
;     for (; pair_ < npair * nrep; pair_ += gridDim.x) { const int pair = pair_ % npair;
;         ATT_DECODE(pair)
;         __syncthreads();
; #pragma unroll
;         for (int it = 0; it < 5; ++it) { const int chunkid = tid + 512 * it; if (chunkid < AKR * 8) { const int key = chunkid >> 3, part = chunkid & 7;
;             *(u32x4*)(Ks + key * KST + part * 8) = kreg[it]; *(u32x4*)(Vs + key * VSR + part * 8) = vreg[it]; } }
;         if (tid < 129) bs[tid] = bn;
;         bf16x8 qf[2]; qf[0] = qn[0]; qf[1] = qn[1];
;         __syncthreads();
;         if (pair_ + (int)gridDim.x < npair * nrep) ATT_PREFETCH((pair_ + (int)gridDim.x) % npair);
;         const int hoff = 64 * half;
;         const int qi = qs * 16 + r16; const int qp = n * 64 + qi; const size_t qtok = brow + ((size_t)qp << dsh) + res;
;         int lo = -64, hi = 64;
;         if (n == 0) lo = max(-64, -qi);
;         if (n == nbk - 1) hi = min(64, 63 - qi);
;         const int cbase = 4 * g4 - r16 - 64;
;         const unsigned ub = (unsigned)(cbase - lo), rng = (unsigned)(hi - lo);
;         const float* bl = bs + (cbase + 64);
.LBB0_47:
	s_and_b64 vcc, exec, s[0:1]
	s_cbranch_vccnz .LBB0_150
	s_add_u32 s0, s12, 0x1ac00000
	v_mov_b32_e32 v41, v185
	s_addc_u32 s1, s5, 0
	s_movk_i32 s5, 0x81
	v_lshl_add_u64 v[88:89], s[6:7], 0, v[40:41]
	v_lshlrev_b32_e32 v41, 4, v46
	v_lshlrev_b32_e32 v46, 2, v44
	v_cmp_gt_i32_e64 s[8:9], s5, v102
	v_readlane_b32 s5, v255, 27
	v_lshlrev_b32_e32 v47, 6, v103
	v_sub_u32_e32 v56, v46, v45
	v_or_b32_e32 v106, v41, v45
	v_bitop3_b32 v108, v41, 63, v45 bitop3:0x36
	v_subrev_u32_e32 v109, 64, v56
	v_lshl_add_u32 v110, v56, 2, s5
	v_or3_b32 v56, v45, v47, v41
	v_lshrrev_b32_e32 v45, 2, v45
	v_or_b32_e32 v45, v47, v45
	v_lshlrev_b32_e32 v43, 3, v102
	v_or3_b32 v41, v45, v41, v46
	s_movk_i32 s24, 0x90
	v_add_u32_e32 v42, 0, v40
	v_mul_lo_u32 v41, v41, s24
	v_and_b32_e32 v43, 24, v43
	v_add3_u32 v111, 0, v41, v43
	v_mad_u64_u32 v[90:91], s[14:15], v104, s24, v[42:43]
	v_add_u32_e32 v41, 0x200, v102
	v_ashrrev_i32_e32 v91, 3, v41
	v_lshl_add_u32 v105, v102, 2, s5
	v_mov_b32_e32 v181, 0xf149f2ca
	v_cmp_gt_u32_e32 vcc, 16, v102
	s_and_saveexec_b64 s[98:99], vcc
	ds_write_b32 v105, v181
	s_mov_b64 exec, s[98:99]
	v_subrev_u32_e32 v182, 16, v102
	v_cmp_gt_u32_e32 vcc, 16, v182
	s_and_saveexec_b64 s[98:99], vcc
	ds_write_b32 v105, v181 offset:516
	s_mov_b64 exec, s[98:99]
	v_add_u32_e32 v105, 64, v105
	v_add_u32_e32 v110, 64, v110
	s_movk_i32 s5, 0x880
	v_mad_u64_u32 v[92:93], s[16:17], v91, s24, v[42:43]
	v_add_u32_e32 v41, 0x400, v102
	v_cmp_gt_i32_e64 s[12:13], s5, v102
	s_movk_i32 s5, 0x680
	v_ashrrev_i32_e32 v93, 3, v41
	v_cmp_gt_i32_e64 s[14:15], s5, v102
	s_movk_i32 s5, 0x480
	v_mad_u64_u32 v[94:95], s[18:19], v93, s24, v[42:43]
	v_add_u32_e32 v41, 0x600, v102
	v_cmp_gt_i32_e64 s[16:17], s5, v102
	s_movk_i32 s5, 0x280
	v_ashrrev_i32_e32 v95, 3, v41
	v_cmp_gt_i32_e64 s[18:19], s5, v102
	v_mad_u64_u32 v[96:97], s[20:21], v95, s24, v[42:43]
	s_movk_i32 s5, 0x80
	v_cmp_gt_i32_e64 s[20:21], s5, v102
	s_movk_i32 s5, 0x100
	v_cmp_gt_i32_e32 vcc, s5, v104
	s_and_b64 s[42:43], s[12:13], vcc
	v_cmp_gt_i32_e32 vcc, s5, v91
	v_add_u32_e32 v41, 0x800, v102
	s_and_b64 s[44:45], s[14:15], vcc
	v_cmp_gt_i32_e32 vcc, s5, v93
	v_ashrrev_i32_e32 v97, 3, v41
	s_and_b64 s[46:47], s[16:17], vcc
	v_cmp_gt_i32_e32 vcc, s5, v95
	v_lshlrev_b32_e32 v40, 3, v44
	v_lshl_add_u32 v57, v44, 4, 0
	v_mad_u64_u32 v[98:99], s[22:23], v97, s24, v[42:43]
	s_and_b64 s[48:49], s[18:19], vcc
	v_cmp_gt_i32_e32 vcc, s5, v97
	v_mul_lo_u32 v41, v56, s24
	v_sub_u32_e32 v107, 0, v106
	v_cmp_eq_u32_e64 s[10:11], 0, v44
	s_and_b64 s[50:51], s[20:21], vcc
	v_lshlrev_b32_e32 v184, 1, v40
	v_add_u32_e32 v99, v57, v41
	v_lshlrev_b32_e32 v100, 1, v46
	s_mov_b32 s24, s2
	s_branch .LBB0_50

; __device__ void attn_phase(unsigned char* smem, const Params& p, int chunk) {
;     ...
;         int lo = -64, hi = 64;
;         if (n == 0) lo = max(-64, -qi);
;         if (n == nbk - 1) hi = min(64, 63 - qi);
;         const int cbase = 4 * g4 - r16 - 64;
;         const unsigned ub = (unsigned)(cbase - lo), rng = (unsigned)(hi - lo);
;         const float* bl = bs + (cbase + 64);
;         f32x4 s[10];
; #pragma unroll
;         for (int kt = 0; kt < 9; ++kt) { s[kt] = (f32x4){0.f, 0.f, 0.f, 0.f};
; #pragma unroll
;             for (int ks = 0; ks < 2; ++ks) { const bf16x8 kfr = *(const bf16x8*)(Ks + (hoff + qs * 16 + kt * 16 + r16) * KST + ks * 32 + g4 * 8); s[kt] = __builtin_amdgcn_mfma_f32_16x16x32_bf16(kfr, qf[ks], s[kt], 0, 0, 0); } }
;         s[9] = (f32x4){0.f, 0.f, 0.f, 0.f};
;         float mx = -1e30f;
; #pragma unroll
;         for (int kt = 0; kt < 9; ++kt)
; #pragma unroll
;             for (int i = 0; i < 4; ++i) { const bool valid = (ub + (unsigned)(16 * kt + i)) <= rng;
;                 const float v = valid ? __builtin_fmaf(s[kt][i], 0.125f * 1.4426950408889634f, bl[16 * kt + i]) : -1e30f; s[kt][i] = v; mx = fmaxf(mx, v); }
.LBB0_76:
	ds_read_b128 v[56:59], v99
	ds_read_b128 v[60:63], v99 offset:64
	ds_read_b128 v[64:67], v99 offset:2304
	ds_read_b128 v[68:71], v99 offset:2368
	ds_read_b128 v[72:75], v99 offset:4608
	s_mul_hi_i32 s31, s24, 0x2aaaaaab
	s_waitcnt lgkmcnt(4)
	v_mfma_f32_16x16x32_bf16 v[56:59], v[56:59], v[52:55], 0
	s_lshr_b32 s34, s31, 31
	s_lshr_b32 s31, s31, 10
	s_add_i32 s31, s31, s34
	s_waitcnt lgkmcnt(3)
	v_mfma_f32_16x16x32_bf16 v[84:87], v[60:63], v[48:51], v[56:59]
	ds_read_b128 v[60:63], v99 offset:6912
	s_mulk_i32 s31, 0x1800
	s_sub_i32 s34, s24, s31
	ds_read_b128 v[56:59], v99 offset:4672
	s_waitcnt lgkmcnt(4)
	v_mfma_f32_16x16x32_bf16 v[64:67], v[64:67], v[52:55], 0
	s_bfe_i32 s35, s34, 0x100004
	s_mulk_i32 s35, 0x2aab
	s_lshr_b32 s36, s35, 31
	s_waitcnt lgkmcnt(3)
	v_mfma_f32_16x16x32_bf16 v[80:83], v[68:71], v[48:51], v[64:67]
	ds_read_b128 v[68:71], v99 offset:6976
	s_lshr_b32 s35, s35, 18
	s_lshl_b32 s24, s34, 1
	s_waitcnt lgkmcnt(3)
	v_mfma_f32_16x16x32_bf16 v[64:67], v[72:75], v[52:55], 0
	ds_read_b128 v[114:117], v99 offset:11584
	s_add_i32 s35, s35, s36
	s_and_b32 s31, s24, 30
	s_waitcnt lgkmcnt(2)
	v_mfma_f32_16x16x32_bf16 v[76:79], v[56:59], v[48:51], v[64:67]
	ds_read_b128 v[56:59], v99 offset:9216
	s_lshr_b32 s24, s34, 4
	s_mul_i32 s35, s35, 24
	ds_read_b128 v[64:67], v99 offset:9280
	v_mfma_f32_16x16x32_bf16 v[60:63], v[60:63], v[52:55], 0
	ds_read_b128 v[118:121], v99 offset:13888
	s_sub_i32 s24, s24, s35
	s_sext_i32_i16 s52, s24
	s_waitcnt lgkmcnt(2)
	v_mfma_f32_16x16x32_bf16 v[56:59], v[56:59], v[52:55], 0
	ds_read_b128 v[122:125], v99 offset:16192
	s_ashr_i32 s24, s52, 2
	s_and_b32 s24, s24, -2
	v_mfma_f32_16x16x32_bf16 v[72:75], v[68:71], v[48:51], v[60:63]
	s_lshr_b32 s35, 32, s24
	s_add_i32 s35, s35, -1
	s_and_b32 s36, s35, s31
	ds_read_b128 v[60:63], v99 offset:11520
	s_waitcnt lgkmcnt(3)
	v_mfma_f32_16x16x32_bf16 v[68:71], v[64:67], v[48:51], v[56:59]
	ds_read_b128 v[126:129], v99 offset:18496
	v_add_u32_e32 v101, s36, v103
	v_not_b32_e32 v113, 63
	ds_read_b128 v[56:59], v99 offset:13824
	s_waitcnt lgkmcnt(2)
	v_mfma_f32_16x16x32_bf16 v[60:63], v[60:63], v[52:55], 0
	v_cmp_eq_u32_e32 vcc, 0, v101
	s_waitcnt lgkmcnt(0)
	v_mfma_f32_16x16x32_bf16 v[56:59], v[56:59], v[52:55], 0
	v_cndmask_b32_e32 v113, v113, v107, vcc
	v_cmp_eq_u32_e32 vcc, s35, v101
	v_mfma_f32_16x16x32_bf16 v[64:67], v[114:117], v[48:51], v[60:63]
	ds_read_b128 v[114:117], v99 offset:16128
	v_mfma_f32_16x16x32_bf16 v[60:63], v[118:121], v[48:51], v[56:59]
	ds_read_b128 v[118:121], v99 offset:18432
	s_waitcnt lgkmcnt(1)
	v_mfma_f32_16x16x32_bf16 v[56:59], v[114:117], v[52:55], 0
	v_cndmask_b32_e32 v114, 64, v108, vcc
	v_sub_u32_e32 v115, v109, v113
	v_sub_u32_e32 v116, v114, v113
	s_waitcnt lgkmcnt(0)
	v_mfma_f32_16x16x32_bf16 v[52:55], v[118:121], v[52:55], 0
	ds_read_b32 v142, v110
	ds_read_b32 v143, v110 offset:4
	ds_read_b32 v144, v110 offset:8
	ds_read_b32 v145, v110 offset:12
	ds_read_b32 v146, v110 offset:64
	ds_read_b32 v147, v110 offset:68
	ds_read_b32 v148, v110 offset:72
	ds_read_b32 v149, v110 offset:76
	ds_read_b32 v150, v110 offset:128
	ds_read_b32 v151, v110 offset:132
	ds_read_b32 v152, v110 offset:136
	ds_read_b32 v153, v110 offset:140
	ds_read_b32 v154, v110 offset:192
	ds_read_b32 v155, v110 offset:196
	ds_read_b32 v156, v110 offset:200
	ds_read_b32 v157, v110 offset:204
	ds_read_b32 v158, v110 offset:256
	ds_read_b32 v159, v110 offset:260
	ds_read_b32 v160, v110 offset:264
	ds_read_b32 v161, v110 offset:268
	ds_read_b32 v162, v110 offset:320
	ds_read_b32 v163, v110 offset:324
	ds_read_b32 v164, v110 offset:328
	ds_read_b32 v165, v110 offset:332
	ds_read_b32 v166, v110 offset:384
	ds_read_b32 v167, v110 offset:388
	ds_read_b32 v168, v110 offset:392
	ds_read_b32 v169, v110 offset:396
	ds_read_b32 v170, v110 offset:448
	ds_read_b32 v171, v110 offset:452
	ds_read_b32 v172, v110 offset:456
	ds_read_b32 v173, v110 offset:460
	ds_read_b32 v174, v110 offset:512
	ds_read_b32 v175, v110 offset:516
	ds_read_b32 v176, v110 offset:520
	ds_read_b32 v177, v110 offset:524
	v_mfma_f32_16x16x32_bf16 v[56:59], v[122:125], v[48:51], v[56:59]
	v_mfma_f32_16x16x32_bf16 v[48:51], v[126:129], v[48:51], v[52:55]
	v_mov_b32_e32 v179, 0xf149f2ca
	s_waitcnt lgkmcnt(0)
	v_readfirstlane_b32 s98, v101
	s_cmp_eq_u32 s98, 0
	s_cbranch_scc1 .Latt_edge
	s_cmp_eq_u32 s98, s35
	s_cbranch_scc1 .Latt_edge
	v_fmamk_f32 v114, v84, 0x3e38aa3b, v142
	v_fmamk_f32 v113, v85, 0x3e38aa3b, v143
	v_fmamk_f32 v85, v86, 0x3e38aa3b, v144
	v_fmamk_f32 v84, v87, 0x3e38aa3b, v145
	v_fmamk_f32 v87, v80, 0x3e38aa3b, v146
	v_fmamk_f32 v86, v81, 0x3e38aa3b, v147
	v_fmamk_f32 v81, v82, 0x3e38aa3b, v148
	v_fmamk_f32 v80, v83, 0x3e38aa3b, v149
	v_fmamk_f32 v83, v76, 0x3e38aa3b, v150
	v_fmamk_f32 v82, v77, 0x3e38aa3b, v151
	v_fmamk_f32 v77, v78, 0x3e38aa3b, v152
	v_fmamk_f32 v76, v79, 0x3e38aa3b, v153
	v_fmamk_f32 v79, v72, 0x3e38aa3b, v154
	v_fmamk_f32 v78, v73, 0x3e38aa3b, v155
	v_fmamk_f32 v73, v74, 0x3e38aa3b, v156
	v_fmamk_f32 v72, v75, 0x3e38aa3b, v157
	v_fmamk_f32 v75, v68, 0x3e38aa3b, v158
	v_fmamk_f32 v74, v69, 0x3e38aa3b, v159
	v_fmamk_f32 v69, v70, 0x3e38aa3b, v160
	v_fmamk_f32 v68, v71, 0x3e38aa3b, v161
	v_fmamk_f32 v71, v64, 0x3e38aa3b, v162
	v_fmamk_f32 v70, v65, 0x3e38aa3b, v163
	v_fmamk_f32 v118, v66, 0x3e38aa3b, v164
	v_fmamk_f32 v117, v67, 0x3e38aa3b, v165
	v_fmamk_f32 v65, v60, 0x3e38aa3b, v166
	v_fmamk_f32 v64, v61, 0x3e38aa3b, v167
	v_fmamk_f32 v66, v62, 0x3e38aa3b, v168
	v_fmamk_f32 v60, v63, 0x3e38aa3b, v169
	v_fmamk_f32 v62, v56, 0x3e38aa3b, v170
	v_fmamk_f32 v61, v57, 0x3e38aa3b, v171
	v_fmamk_f32 v55, v58, 0x3e38aa3b, v172
	v_fmamk_f32 v54, v59, 0x3e38aa3b, v173
	v_fmamk_f32 v56, v48, 0x3e38aa3b, v174
	v_fmamk_f32 v52, v49, 0x3e38aa3b, v175
	v_fmamk_f32 v53, v50, 0x3e38aa3b, v176
	v_fmamk_f32 v49, v51, 0x3e38aa3b, v177
	s_branch .Latt_join
; __device__ void attn_phase(unsigned char* smem, const Params& p, int chunk) {
;     ...
;         for (int kt = 0; kt < 9; ++kt)
; #pragma unroll
;             for (int i = 0; i < 4; ++i) { const bool valid = (ub + (unsigned)(16 * kt + i)) <= rng;
;                 const float v = valid ? __builtin_fmaf(s[kt][i], 0.125f * 1.4426950408889634f, bl[16 * kt + i]) : -1e30f; s[kt][i] = v; mx = fmaxf(mx, v); }
.Latt_edge:
	v_add_u32_e32 v180, 1, v115
	v_cmp_le_u32_e32 vcc, v115, v116
	v_cmp_le_u32_e64 s[98:99], v180, v116
	v_fmac_f32_e32 v142, 0x3e38aa3b, v84
	v_fmac_f32_e32 v143, 0x3e38aa3b, v85
	v_cndmask_b32_e32 v114, v179, v142, vcc
	v_cndmask_b32_e64 v113, v179, v143, s[98:99]
	v_add_u32_e32 v178, 2, v115
	v_add_u32_e32 v180, 3, v115
	v_cmp_le_u32_e32 vcc, v178, v116
	v_cmp_le_u32_e64 s[98:99], v180, v116
	v_fmac_f32_e32 v144, 0x3e38aa3b, v86
	v_fmac_f32_e32 v145, 0x3e38aa3b, v87
	v_cndmask_b32_e32 v85, v179, v144, vcc
	v_cndmask_b32_e64 v84, v179, v145, s[98:99]
	v_add_u32_e32 v178, 16, v115
	v_add_u32_e32 v180, 17, v115
	v_cmp_le_u32_e32 vcc, v178, v116
	v_cmp_le_u32_e64 s[98:99], v180, v116
	v_fmac_f32_e32 v146, 0x3e38aa3b, v80
	v_fmac_f32_e32 v147, 0x3e38aa3b, v81
	v_cndmask_b32_e32 v87, v179, v146, vcc
	v_cndmask_b32_e64 v86, v179, v147, s[98:99]
	v_add_u32_e32 v178, 18, v115
	v_add_u32_e32 v180, 19, v115
	v_cmp_le_u32_e32 vcc, v178, v116
	v_cmp_le_u32_e64 s[98:99], v180, v116
	v_fmac_f32_e32 v148, 0x3e38aa3b, v82
	v_fmac_f32_e32 v149, 0x3e38aa3b, v83
	v_cndmask_b32_e32 v81, v179, v148, vcc
	v_cndmask_b32_e64 v80, v179, v149, s[98:99]
	v_add_u32_e32 v178, 32, v115
	v_add_u32_e32 v180, 33, v115
	v_cmp_le_u32_e32 vcc, v178, v116
	v_cmp_le_u32_e64 s[98:99], v180, v116
	v_fmac_f32_e32 v150, 0x3e38aa3b, v76
	v_fmac_f32_e32 v151, 0x3e38aa3b, v77
	v_cndmask_b32_e32 v83, v179, v150, vcc
	v_cndmask_b32_e64 v82, v179, v151, s[98:99]
	v_add_u32_e32 v178, 34, v115
	v_add_u32_e32 v180, 35, v115
	v_cmp_le_u32_e32 vcc, v178, v116
	v_cmp_le_u32_e64 s[98:99], v180, v116
	v_fmac_f32_e32 v152, 0x3e38aa3b, v78
	v_fmac_f32_e32 v153, 0x3e38aa3b, v79
	v_cndmask_b32_e32 v77, v179, v152, vcc
	v_cndmask_b32_e64 v76, v179, v153, s[98:99]
	v_add_u32_e32 v178, 48, v115
	v_add_u32_e32 v180, 49, v115
	v_cmp_le_u32_e32 vcc, v178, v116
	v_cmp_le_u32_e64 s[98:99], v180, v116
	v_fmac_f32_e32 v154, 0x3e38aa3b, v72
	v_fmac_f32_e32 v155, 0x3e38aa3b, v73
	v_cndmask_b32_e32 v79, v179, v154, vcc
	v_cndmask_b32_e64 v78, v179, v155, s[98:99]
	v_add_u32_e32 v178, 50, v115
	v_add_u32_e32 v180, 51, v115
	v_cmp_le_u32_e32 vcc, v178, v116
	v_cmp_le_u32_e64 s[98:99], v180, v116
	v_fmac_f32_e32 v156, 0x3e38aa3b, v74
	v_fmac_f32_e32 v157, 0x3e38aa3b, v75
	v_cndmask_b32_e32 v73, v179, v156, vcc
	v_cndmask_b32_e64 v72, v179, v157, s[98:99]
	v_add_u32_e32 v178, 64, v115
	v_add_u32_e32 v180, 0x41, v115
	v_cmp_le_u32_e32 vcc, v178, v116
	v_cmp_le_u32_e64 s[98:99], v180, v116
	v_fmac_f32_e32 v158, 0x3e38aa3b, v68
	v_fmac_f32_e32 v159, 0x3e38aa3b, v69
	v_cndmask_b32_e32 v75, v179, v158, vcc
	v_cndmask_b32_e64 v74, v179, v159, s[98:99]
	v_add_u32_e32 v178, 0x42, v115
	v_add_u32_e32 v180, 0x43, v115
	v_cmp_le_u32_e32 vcc, v178, v116
	v_cmp_le_u32_e64 s[98:99], v180, v116
	v_fmac_f32_e32 v160, 0x3e38aa3b, v70
	v_fmac_f32_e32 v161, 0x3e38aa3b, v71
	v_cndmask_b32_e32 v69, v179, v160, vcc
	v_cndmask_b32_e64 v68, v179, v161, s[98:99]
	v_add_u32_e32 v178, 0x50, v115
	v_add_u32_e32 v180, 0x51, v115
	v_cmp_le_u32_e32 vcc, v178, v116
	v_cmp_le_u32_e64 s[98:99], v180, v116
	v_fmac_f32_e32 v162, 0x3e38aa3b, v64
	v_fmac_f32_e32 v163, 0x3e38aa3b, v65
	v_cndmask_b32_e32 v71, v179, v162, vcc
	v_cndmask_b32_e64 v70, v179, v163, s[98:99]
	v_add_u32_e32 v178, 0x52, v115
	v_add_u32_e32 v180, 0x53, v115
	v_cmp_le_u32_e32 vcc, v178, v116
	v_cmp_le_u32_e64 s[98:99], v180, v116
	v_fmac_f32_e32 v164, 0x3e38aa3b, v66
	v_fmac_f32_e32 v165, 0x3e38aa3b, v67
	v_cndmask_b32_e32 v118, v179, v164, vcc
	v_cndmask_b32_e64 v117, v179, v165, s[98:99]
	v_add_u32_e32 v178, 0x60, v115
	v_add_u32_e32 v180, 0x61, v115
	v_cmp_le_u32_e32 vcc, v178, v116
	v_cmp_le_u32_e64 s[98:99], v180, v116
	v_fmac_f32_e32 v166, 0x3e38aa3b, v60
	v_fmac_f32_e32 v167, 0x3e38aa3b, v61
	v_cndmask_b32_e32 v65, v179, v166, vcc
	v_cndmask_b32_e64 v64, v179, v167, s[98:99]
	v_add_u32_e32 v178, 0x62, v115
	v_add_u32_e32 v180, 0x63, v115
	v_cmp_le_u32_e32 vcc, v178, v116
	v_cmp_le_u32_e64 s[98:99], v180, v116
	v_fmac_f32_e32 v168, 0x3e38aa3b, v62
	v_fmac_f32_e32 v169, 0x3e38aa3b, v63
	v_cndmask_b32_e32 v66, v179, v168, vcc
	v_cndmask_b32_e64 v60, v179, v169, s[98:99]
	v_add_u32_e32 v178, 0x70, v115
	v_add_u32_e32 v180, 0x71, v115
	v_cmp_le_u32_e32 vcc, v178, v116
	v_cmp_le_u32_e64 s[98:99], v180, v116
	v_fmac_f32_e32 v170, 0x3e38aa3b, v56
	v_fmac_f32_e32 v171, 0x3e38aa3b, v57
	v_cndmask_b32_e32 v62, v179, v170, vcc
	v_cndmask_b32_e64 v61, v179, v171, s[98:99]
	v_add_u32_e32 v178, 0x72, v115
	v_add_u32_e32 v180, 0x73, v115
	v_cmp_le_u32_e32 vcc, v178, v116
	v_cmp_le_u32_e64 s[98:99], v180, v116
	v_fmac_f32_e32 v172, 0x3e38aa3b, v58
	v_fmac_f32_e32 v173, 0x3e38aa3b, v59
	v_cndmask_b32_e32 v55, v179, v172, vcc
	v_cndmask_b32_e64 v54, v179, v173, s[98:99]
	v_add_u32_e32 v178, 0x80, v115
	v_add_u32_e32 v180, 0x81, v115
	v_cmp_le_u32_e32 vcc, v178, v116
	v_cmp_le_u32_e64 s[98:99], v180, v116
	v_fmac_f32_e32 v174, 0x3e38aa3b, v48
	v_fmac_f32_e32 v175, 0x3e38aa3b, v49
	v_cndmask_b32_e32 v56, v179, v174, vcc
	v_cndmask_b32_e64 v52, v179, v175, s[98:99]
	v_add_u32_e32 v178, 0x82, v115
	v_add_u32_e32 v180, 0x83, v115
	v_cmp_le_u32_e32 vcc, v178, v116
	v_cmp_le_u32_e64 s[98:99], v180, v116
	v_fmac_f32_e32 v176, 0x3e38aa3b, v50
	v_fmac_f32_e32 v177, 0x3e38aa3b, v51
	v_cndmask_b32_e32 v53, v179, v176, vcc
	v_cndmask_b32_e64 v49, v179, v177, s[98:99]
; #define LAS __attribute__((address_space(3)))
; __device__ __forceinline__ unsigned cvt_pk_bf16(float lo, float hi) { const f32x2_t v = {lo, hi}; const bf16x2_t b = __builtin_convertvector(v, bf16x2_t); return __builtin_bit_cast(unsigned, b); }
; __device__ void attn_phase(unsigned char* smem, const Params& p, int chunk) {
;     ...
;         float mx = -1e30f;
; #pragma unroll
;         for (int kt = 0; kt < 9; ++kt)
; #pragma unroll
;             for (int i = 0; i < 4; ++i) { const bool valid = (ub + (unsigned)(16 * kt + i)) <= rng;
;                 const float v = valid ? __builtin_fmaf(s[kt][i], 0.125f * 1.4426950408889634f, bl[16 * kt + i]) : -1e30f; s[kt][i] = v; mx = fmaxf(mx, v); }
;         mx = fmaxf(mx, __shfl_xor(mx, 16)); mx = fmaxf(mx, __shfl_xor(mx, 32));
;         float den = 0.f;
; #pragma unroll
;         for (int kt = 0; kt < 9; ++kt)
; #pragma unroll
;             for (int i = 0; i < 4; ++i) { const float e = __builtin_amdgcn_exp2f(s[kt][i] - mx); s[kt][i] = e; den += e; }
;         den += __shfl_xor(den, 16); den += __shfl_xor(den, 32);
;         f32x4 o[4];
; #pragma unroll
;         for (int et = 0; et < 4; ++et) o[et] = (f32x4){0.f, 0.f, 0.f, 0.f};
;         const bf16_t* vbase = Vs + (hoff + qs * 16 + 4 * g4 + (r16 >> 2)) * VSR + 4 * (r16 & 3);
; #pragma unroll
;         for (int cc = 0; cc < 5; ++cc) {
;             union { u32x4 u; bf16x8 v; } pf; pf.u.x = cvt_pk_bf16(s[2 * cc][0], s[2 * cc][1]); pf.u.y = cvt_pk_bf16(s[2 * cc][2], s[2 * cc][3]);
;             pf.u.z = cvt_pk_bf16(s[2 * cc + 1][0], s[2 * cc + 1][1]); pf.u.w = cvt_pk_bf16(s[2 * cc + 1][2], s[2 * cc + 1][3]);
; #pragma unroll
;             for (int et = 0; et < 4; ++et) { const bf16_t* vp = vbase + (cc * 32) * VSR + et * 16;
;                 const s16x4 v0 = __builtin_amdgcn_ds_read_tr16_b64_v4i16((LAS s16x4*)(LAS unsigned char*)vp), v1 = __builtin_amdgcn_ds_read_tr16_b64_v4i16((LAS s16x4*)(LAS unsigned char*)(vp + 16 * VSR));
;                 const bf16x8 vf = {v0[0], v0[1], v0[2], v0[3], v1[0], v1[1], v1[2], v1[3]};
;                 o[et] = __builtin_amdgcn_mfma_f32_16x16x32_bf16(vf, pf.v, o[et], 0, 0, 0); } }
.Latt_join:
	s_mov_b32 s35, 0xf149f2ca
	v_max3_f32 v48, v114, s35, v113
	v_max3_f32 v48, v48, v85, v84
	v_max3_f32 v48, v48, v87, v86
	v_max3_f32 v48, v48, v81, v80
	v_max3_f32 v48, v48, v83, v82
	v_max3_f32 v48, v48, v77, v76
	v_max3_f32 v48, v48, v79, v78
	v_max3_f32 v48, v48, v73, v72
	v_max3_f32 v48, v48, v75, v74
	v_max3_f32 v48, v48, v69, v68
	v_max3_f32 v48, v48, v71, v70
	v_max3_f32 v48, v48, v118, v117
	v_max3_f32 v48, v48, v65, v64
	v_max3_f32 v48, v48, v66, v60
	v_max3_f32 v48, v48, v62, v61
	v_max3_f32 v48, v48, v55, v54
	v_max3_f32 v48, v48, v56, v52
	v_and_b32_e32 v51, 64, v243
	v_max3_f32 v50, v48, v53, v49
	v_xor_b32_e32 v48, 16, v243
	v_add_u32_e32 v51, 64, v51
	v_cmp_lt_i32_e32 vcc, v48, v51
	s_mulk_i32 s34, 0x2aab
	s_lshr_b32 s35, s34, 31
	v_cndmask_b32_e32 v48, v243, v48, vcc
	v_lshlrev_b32_e32 v48, 2, v48
	ds_bpermute_b32 v57, v48, v50
	s_ashr_i32 s34, s34, 22
	s_add_i32 s34, s34, s35
	s_sub_i32 s35, 5, s24
	s_bfe_i64 s[58:59], s[34:35], 0x100000
	s_waitcnt lgkmcnt(0)
	v_max_f32_e32 v57, v57, v57
	v_max_f32_e32 v50, v50, v57
	v_xor_b32_e32 v57, 32, v243
	v_cmp_lt_i32_e32 vcc, v57, v51
	s_lshr_b32 s31, s31, s35
	s_lshl_b64 s[34:35], s[58:59], 11
	v_cndmask_b32_e32 v51, v243, v57, vcc
	v_lshlrev_b32_e32 v51, 2, v51
	ds_bpermute_b32 v57, v51, v50
	s_or_b32 s34, s34, s31
	s_waitcnt lgkmcnt(0)
	v_max_f32_e32 v57, v57, v57
	v_max_f32_e32 v50, v50, v57
	v_sub_f32_e32 v57, v114, v50
	v_exp_f32_e32 v57, v57
	v_sub_f32_e32 v58, v113, v50
	v_exp_f32_e32 v58, v58
	v_sub_f32_e32 v59, v85, v50
	v_exp_f32_e32 v59, v59
	v_sub_f32_e32 v63, v84, v50
	v_exp_f32_e32 v63, v63
	v_sub_f32_e32 v84, v87, v50
	v_add_f32_e32 v67, 0, v57
	v_exp_f32_e32 v84, v84
	v_sub_f32_e32 v85, v86, v50
	v_add_f32_e32 v67, v58, v67
	v_exp_f32_e32 v85, v85
	v_sub_f32_e32 v81, v81, v50
	v_add_f32_e32 v67, v59, v67
	v_exp_f32_e32 v81, v81
	v_sub_f32_e32 v80, v80, v50
	v_add_f32_e32 v67, v63, v67
	v_exp_f32_e32 v80, v80
	v_sub_f32_e32 v83, v83, v50
	v_add_f32_e32 v67, v84, v67
	v_exp_f32_e32 v113, v83
	v_sub_f32_e32 v82, v82, v50
	v_add_f32_e32 v67, v85, v67
	v_exp_f32_e32 v114, v82
	v_sub_f32_e32 v77, v77, v50
	v_add_f32_e32 v67, v81, v67
	v_exp_f32_e32 v115, v77
	v_sub_f32_e32 v76, v76, v50
	v_add_f32_e32 v67, v80, v67
	v_exp_f32_e32 v116, v76
	v_sub_f32_e32 v76, v79, v50
	v_add_f32_e32 v67, v113, v67
	v_exp_f32_e32 v119, v76
	v_sub_f32_e32 v76, v78, v50
	v_add_f32_e32 v67, v114, v67
	v_exp_f32_e32 v120, v76
	v_sub_f32_e32 v73, v73, v50
	v_add_f32_e32 v67, v115, v67
	v_exp_f32_e32 v121, v73
	v_sub_f32_e32 v72, v72, v50
	v_add_f32_e32 v67, v116, v67
	v_exp_f32_e32 v122, v72
	v_sub_f32_e32 v72, v75, v50
	v_add_f32_e32 v67, v119, v67
	v_exp_f32_e32 v126, v72
	v_sub_f32_e32 v72, v74, v50
	v_add_f32_e32 v67, v120, v67
	v_exp_f32_e32 v127, v72
	v_sub_f32_e32 v69, v69, v50
	v_add_f32_e32 v67, v121, v67
	v_exp_f32_e32 v128, v69
	v_sub_f32_e32 v68, v68, v50
	v_add_f32_e32 v67, v122, v67
	v_exp_f32_e32 v129, v68
	v_sub_f32_e32 v68, v71, v50
	v_add_f32_e32 v67, v126, v67
	v_exp_f32_e32 v130, v68
	v_sub_f32_e32 v68, v70, v50
	v_add_f32_e32 v67, v127, v67
	v_exp_f32_e32 v131, v68
	v_sub_f32_e32 v68, v118, v50
	v_add_f32_e32 v67, v128, v67
	v_exp_f32_e32 v132, v68
	v_sub_f32_e32 v68, v117, v50
	v_add_f32_e32 v67, v129, v67
	v_exp_f32_e32 v133, v68
	v_cvt_pk_bf16_f32 v68, v57, v58
	ds_read_b64_tr_b16 v[74:75], v111 offset:41472
	ds_read_b64_tr_b16 v[72:73], v111 offset:39168
	v_cvt_pk_bf16_f32 v70, v84, v85
	v_cvt_pk_bf16_f32 v71, v81, v80
	ds_read_b64_tr_b16 v[78:79], v111 offset:41504
	ds_read_b64_tr_b16 v[76:77], v111 offset:39200
	ds_read_b64_tr_b16 v[80:81], v111 offset:39232
	ds_read_b64_tr_b16 v[84:85], v111 offset:39264
	ds_read_b64_tr_b16 v[82:83], v111 offset:41536
	ds_read_b64_tr_b16 v[86:87], v111 offset:41568
	v_sub_f32_e32 v57, v65, v50
	v_add_f32_e32 v67, v130, v67
	v_exp_f32_e32 v134, v57
	v_add_f32_e32 v67, v131, v67
	v_add_f32_e32 v67, v132, v67
	v_sub_f32_e32 v57, v64, v50
	v_add_f32_e32 v117, v133, v67
	v_cvt_pk_bf16_f32 v69, v59, v63
	v_exp_f32_e32 v135, v57
	v_sub_f32_e32 v57, v66, v50
	s_waitcnt lgkmcnt(6)
	v_mfma_f32_16x16x32_bf16 v[72:75], v[72:75], v[68:71], 0
	v_exp_f32_e32 v136, v57
	v_add_f32_e32 v57, v134, v117
	v_sub_f32_e32 v58, v60, v50
	s_waitcnt lgkmcnt(4)
	v_mfma_f32_16x16x32_bf16 v[76:79], v[76:79], v[68:71], 0
	v_add_f32_e32 v57, v135, v57
	v_sub_f32_e32 v55, v55, v50
	v_add_f32_e32 v57, v136, v57
	s_waitcnt lgkmcnt(1)
	v_mfma_f32_16x16x32_bf16 v[64:67], v[80:83], v[68:71], 0
	v_cvt_pk_bf16_f32 v80, v113, v114
	v_cvt_pk_bf16_f32 v81, v115, v116
	v_cvt_pk_bf16_f32 v82, v119, v120
	s_waitcnt lgkmcnt(0)
	v_mfma_f32_16x16x32_bf16 v[68:71], v[84:87], v[68:71], 0
	ds_read_b64_tr_b16 v[84:85], v111 offset:43776
	ds_read_b64_tr_b16 v[86:87], v111 offset:46080
	v_cvt_pk_bf16_f32 v83, v121, v122
	ds_read_b64_tr_b16 v[116:117], v111 offset:46112
	ds_read_b64_tr_b16 v[114:115], v111 offset:43808
	ds_read_b64_tr_b16 v[118:119], v111 offset:43840
	ds_read_b64_tr_b16 v[122:123], v111 offset:43872
	ds_read_b64_tr_b16 v[120:121], v111 offset:46144
	ds_read_b64_tr_b16 v[124:125], v111 offset:46176
	v_exp_f32_e32 v113, v58
	v_sub_f32_e32 v58, v62, v50
	v_exp_f32_e32 v137, v58
	v_sub_f32_e32 v58, v61, v50
	s_waitcnt lgkmcnt(6)
	v_mfma_f32_16x16x32_bf16 v[72:75], v[84:87], v[80:83], v[72:75]
	v_exp_f32_e32 v138, v58
	v_sub_f32_e32 v54, v54, v50
	v_add_f32_e32 v57, v113, v57
	s_waitcnt lgkmcnt(4)
	v_mfma_f32_16x16x32_bf16 v[76:79], v[114:117], v[80:83], v[76:79]
	v_add_f32_e32 v57, v137, v57
	v_add_f32_e32 v139, v138, v57
	v_sub_f32_e32 v52, v52, v50
	s_waitcnt lgkmcnt(1)
	v_mfma_f32_16x16x32_bf16 v[58:61], v[118:121], v[80:83], v[64:67]
	v_sub_f32_e32 v49, v49, v50
	v_exp_f32_e32 v49, v49
	s_waitcnt lgkmcnt(0)
; #define LAS __attribute__((address_space(3)))
; __device__ __forceinline__ unsigned cvt_pk_bf16(float lo, float hi) { const f32x2_t v = {lo, hi}; const bf16x2_t b = __builtin_convertvector(v, bf16x2_t); return __builtin_bit_cast(unsigned, b); }
; __device__ void attn_phase(unsigned char* smem, const Params& p, int chunk) {
;     ...
;         for (int cc = 0; cc < 5; ++cc) {
;             union { u32x4 u; bf16x8 v; } pf; pf.u.x = cvt_pk_bf16(s[2 * cc][0], s[2 * cc][1]); pf.u.y = cvt_pk_bf16(s[2 * cc][2], s[2 * cc][3]);
;             pf.u.z = cvt_pk_bf16(s[2 * cc + 1][0], s[2 * cc + 1][1]); pf.u.w = cvt_pk_bf16(s[2 * cc + 1][2], s[2 * cc + 1][3]);
; #pragma unroll
;             for (int et = 0; et < 4; ++et) { const bf16_t* vp = vbase + (cc * 32) * VSR + et * 16;
;                 const s16x4 v0 = __builtin_amdgcn_ds_read_tr16_b64_v4i16((LAS s16x4*)(LAS unsigned char*)vp), v1 = __builtin_amdgcn_ds_read_tr16_b64_v4i16((LAS s16x4*)(LAS unsigned char*)(vp + 16 * VSR));
;                 const bf16x8 vf = {v0[0], v0[1], v0[2], v0[3], v1[0], v1[1], v1[2], v1[3]};
;                 o[et] = __builtin_amdgcn_mfma_f32_16x16x32_bf16(vf, pf.v, o[et], 0, 0, 0); } }
;         const float inv = __builtin_amdgcn_rcpf(den);
;         bf16_t* op = qkv + qtok * QKVC + hh * 64 + 4 * g4;
; #pragma unroll
;         for (int et = 0; et < 4; ++et) { u32x2 wv; wv.x = cvt_pk_bf16(o[et][0] * inv, o[et][1] * inv); wv.y = cvt_pk_bf16(o[et][2] * inv, o[et][3] * inv); *(u32x2*)(op + et * 16) = wv; }
;         if (g4 == 0) lse[qtok * 24 + hh] = mx * 0.6931471805599453f + logf(den);
	v_mfma_f32_16x16x32_bf16 v[62:65], v[122:125], v[80:83], v[68:71]
	ds_read_b64_tr_b16 v[80:81], v111 offset:48384
	ds_read_b64_tr_b16 v[82:83], v111 offset:50688
	v_cvt_pk_bf16_f32 v66, v126, v127
	v_cvt_pk_bf16_f32 v67, v128, v129
	v_cvt_pk_bf16_f32 v68, v130, v131
	v_cvt_pk_bf16_f32 v69, v132, v133
	ds_read_b64_tr_b16 v[86:87], v111 offset:50720
	ds_read_b64_tr_b16 v[84:85], v111 offset:48416
	ds_read_b64_tr_b16 v[114:115], v111 offset:48448
	ds_read_b64_tr_b16 v[118:119], v111 offset:48480
	ds_read_b64_tr_b16 v[116:117], v111 offset:50752
	ds_read_b64_tr_b16 v[120:121], v111 offset:50784
	s_waitcnt lgkmcnt(6)
	v_mfma_f32_16x16x32_bf16 v[70:73], v[80:83], v[66:69], v[72:75]
	v_exp_f32_e32 v80, v55
	s_waitcnt lgkmcnt(4)
	v_mfma_f32_16x16x32_bf16 v[74:77], v[84:87], v[66:69], v[76:79]
	s_nop 2
	v_exp_f32_e32 v78, v54
	v_sub_f32_e32 v54, v56, v50
	v_exp_f32_e32 v86, v54
	s_waitcnt lgkmcnt(1)
	v_mfma_f32_16x16x32_bf16 v[54:57], v[114:117], v[66:69], v[58:61]
	s_nop 2
	v_add_f32_e32 v58, v80, v139
	v_add_f32_e32 v58, v78, v58
	v_add_f32_e32 v87, v86, v58
	s_waitcnt lgkmcnt(0)
	v_mfma_f32_16x16x32_bf16 v[58:61], v[118:121], v[66:69], v[62:65]
	ds_read_b64_tr_b16 v[66:67], v111 offset:52992
	ds_read_b64_tr_b16 v[68:69], v111 offset:55296
	s_nop 0
	v_cvt_pk_bf16_f32 v62, v134, v135
	v_cvt_pk_bf16_f32 v63, v136, v113
	v_cvt_pk_bf16_f32 v64, v137, v138
	v_cvt_pk_bf16_f32 v65, v80, v78
	ds_read_b64_tr_b16 v[80:81], v111 offset:55328
	ds_read_b64_tr_b16 v[78:79], v111 offset:53024
	ds_read_b64_tr_b16 v[82:83], v111 offset:53056
	ds_read_b64_tr_b16 v[114:115], v111 offset:53088
	ds_read_b64_tr_b16 v[84:85], v111 offset:55360
	ds_read_b64_tr_b16 v[116:117], v111 offset:55392
	v_exp_f32_e32 v113, v52
	v_sub_f32_e32 v52, v53, v50
	s_waitcnt lgkmcnt(6)
	v_mfma_f32_16x16x32_bf16 v[66:69], v[66:69], v[62:65], v[70:73]
	s_waitcnt lgkmcnt(4)
	v_mfma_f32_16x16x32_bf16 v[70:73], v[78:81], v[62:65], v[74:77]
	s_nop 2
	v_exp_f32_e32 v74, v52
	s_waitcnt lgkmcnt(1)
	v_mfma_f32_16x16x32_bf16 v[52:55], v[82:85], v[62:65], v[54:57]
	s_nop 2
	v_add_f32_e32 v56, v113, v87
	v_add_f32_e32 v56, v74, v56
	v_add_f32_e32 v87, v49, v56
	s_waitcnt lgkmcnt(0)
	v_mfma_f32_16x16x32_bf16 v[56:59], v[114:117], v[62:65], v[58:61]
	v_mov_b32_e32 v62, v185
	v_mov_b32_e32 v63, v185
	s_nop 0
	v_cvt_pk_bf16_f32 v61, v74, v49
	ds_read_b64_tr_b16 v[74:75], v111 offset:57600
	ds_read_b64_tr_b16 v[76:77], v111 offset:59904
	ds_bpermute_b32 v49, v48, v87
	v_cvt_pk_bf16_f32 v60, v86, v113
	ds_read_b64_tr_b16 v[80:81], v111 offset:59936
	ds_read_b64_tr_b16 v[78:79], v111 offset:57632
	ds_read_b64_tr_b16 v[82:83], v111 offset:57664
	ds_read_b64_tr_b16 v[114:115], v111 offset:57696
	ds_read_b64_tr_b16 v[84:85], v111 offset:59968
	ds_read_b64_tr_b16 v[116:117], v111 offset:60000
	s_waitcnt lgkmcnt(7)
	v_mfma_f32_16x16x32_bf16 v[64:67], v[74:77], v[60:63], v[66:69]
	v_lshl_or_b32 v48, v101, 6, v106
	v_mov_b32_e32 v101, v185
	s_waitcnt lgkmcnt(4)
	v_mfma_f32_16x16x32_bf16 v[68:71], v[78:81], v[60:63], v[70:73]
	s_nop 2
	v_add_f32_e32 v72, v87, v49
	ds_bpermute_b32 v51, v51, v72
	v_ashrrev_i32_e32 v49, 31, v48
	v_lshlrev_b64 v[48:49], s24, v[48:49]
	s_waitcnt lgkmcnt(2)
	v_mfma_f32_16x16x32_bf16 v[52:55], v[82:85], v[60:63], v[52:55]
	v_lshl_add_u64 v[48:49], s[34:35], 0, v[48:49]
	s_waitcnt lgkmcnt(0)
	v_add_f32_e32 v51, v72, v51
	v_mfma_f32_16x16x32_bf16 v[56:59], v[114:117], v[60:63], v[56:59]
	v_mov_b64_e32 v[62:63], s[6:7]
	v_mad_u64_u32 v[62:63], s[34:35], v48, s93, v[62:63]
	v_rcp_f32_e32 v60, v51
	v_mov_b32_e32 v72, v63
	v_mad_u64_u32 v[72:73], s[34:35], v49, s93, v[72:73]
	s_lshl_b32 s34, s52, 6
	v_mov_b32_e32 v63, v72
	s_ashr_i32 s35, s34, 31
	v_lshl_add_u64 v[62:63], s[34:35], 1, v[62:63]
	v_pk_mul_f32 v[64:65], v[60:61], v[64:65] op_sel_hi:[0,1]
	v_pk_mul_f32 v[66:67], v[60:61], v[66:67] op_sel_hi:[0,1]
	v_pk_mul_f32 v[52:53], v[60:61], v[52:53] op_sel_hi:[0,1]
	v_pk_mul_f32 v[54:55], v[60:61], v[54:55] op_sel_hi:[0,1]
	v_lshl_add_u64 v[62:63], v[62:63], 0, v[100:101]
	v_cvt_pk_bf16_f32 v64, v64, v65
	v_cvt_pk_bf16_f32 v65, v66, v67
	v_cvt_pk_bf16_f32 v52, v52, v53
	v_cvt_pk_bf16_f32 v53, v54, v55
	global_store_dwordx2 v[62:63], v[64:65], off
	v_pk_mul_f32 v[64:65], v[60:61], v[68:69] op_sel_hi:[0,1]
	v_pk_mul_f32 v[66:67], v[60:61], v[70:71] op_sel_hi:[0,1]
	global_store_dwordx2 v[62:63], v[52:53], off offset:64
	v_pk_mul_f32 v[52:53], v[60:61], v[56:57] op_sel_hi:[0,1]
	v_pk_mul_f32 v[54:55], v[60:61], v[58:59] op_sel_hi:[0,1]
	v_cvt_pk_bf16_f32 v64, v64, v65
	v_cvt_pk_bf16_f32 v65, v66, v67
	v_cvt_pk_bf16_f32 v52, v52, v53
	v_cvt_pk_bf16_f32 v53, v54, v55
	global_store_dwordx2 v[62:63], v[64:65], off offset:32
	global_store_dwordx2 v[62:63], v[52:53], off offset:96
	s_and_saveexec_b64 s[58:59], s[10:11]
	s_cbranch_execz .LBB0_49
	s_mov_b32 s24, 0x800000
	v_cmp_gt_f32_e32 vcc, s24, v51
	s_mov_b32 s24, 0x3f317217
	s_ashr_i32 s53, s52, 31
	v_cndmask_b32_e64 v52, 0, 32, vcc
	v_ldexp_f32 v51, v51, v52
	v_log_f32_e32 v51, v51
	v_cndmask_b32_e32 v52, 0, v140, vcc
	v_mul_f32_e32 v53, 0x3f317217, v51
	v_fma_f32 v53, v51, s24, -v53
	v_fmac_f32_e32 v53, 0x3377d1cf, v51
	v_fmac_f32_e32 v53, 0x3f317217, v51
	v_cmp_lt_f32_e64 vcc, |v51|, s70
	s_nop 1
	v_cndmask_b32_e32 v51, v51, v53, vcc
	v_sub_f32_e32 v52, v51, v52
	v_fmac_f32_e32 v52, 0x3f317218, v50
	v_mov_b64_e32 v[50:51], s[0:1]
	v_mad_u64_u32 v[50:51], s[34:35], v48, s92, v[50:51]
	v_mov_b32_e32 v48, v51
	v_mad_u64_u32 v[48:49], s[34:35], v49, s92, v[48:49]
	v_mov_b32_e32 v51, v48
	v_lshl_add_u64 v[48:49], s[52:53], 2, v[50:51]
	global_store_dword v[48:49], v52, off
	s_branch .LBB0_49
